# SG unit loads issued in the loop header before the per-unit vss round trip (both HBM latencies overlap)
# speedup vs baseline: 1.0068x; 1.0068x over previous
; __device__ __forceinline__ unsigned cvt_pk_bf16(float lo, float hi) { const f2_t v = {lo, hi}; const bf2_t b = __builtin_convertvector(v, bf2_t); return __builtin_bit_cast(unsigned, b); }
; __device__ __forceinline__ f32x4 mfma16(bf16x8 a, bf16x8 b, f32x4 c) { return __builtin_amdgcn_mfma_f32_16x16x32_bf16(a, b, c, 0, 0, 0); }
; __device__ void sg_phase(int wv, const Params& p, int jl, unsigned char* lds) {
;     ...
;         const float* ws = p.a_w_s + ((size_t)jl * 8 + g) * 128 * 128;
; #pragma unroll
;         for (int ps = 0; ps < 8; ++ps) { const int idx = tid + ps * NTHR, t = idx >> 5, s4 = (idx & 31) * 4;
;             const f32x4 wv = *(const f32x4*)(ws + t * 128 + s4); const f32x4 r4 = *(const f32x4*)(rsL + s4); const f32x4 x = wv * r4;
;             u32x2 pk; pk.x = cvt_pk_bf16(x[0], x[1]); pk.y = cvt_pk_bf16(x[2], x[3]); *(u32x2*)(WsL + t * PW + s4) = pk; }
; #pragma unroll
;         for (int ps = 0; ps < 4; ++ps) { const int idx = tid + ps * NTHR, s = idx & 127, d8 = (idx >> 7) * 8;
;             const bf16x8 v = *(const bf16x8*)(uv + (size_t)(t0 + s) * 2048 + 1024 + g * 128 + d8);
; #pragma unroll
;             for (int e = 0; e < 8; ++e) VTL[(d8 + e) * PW + s] = (bf16_t)v[e]; }
;         __syncthreads();
;         bf16x8 af[4];
; #pragma unroll
;         for (int kk = 0; kk < 4; ++kk) af[kk] = *(const bf16x8*)(WsL + (16 * w + lr) * PW + 32 * kk + 8 * lq);
;         const int tok = t0 + 16 * w + lr; const float bs = p.a_b_s[((size_t)jl * 8 + g) * 128 + 16 * w + lr];
; #pragma unroll
;         for (int db = 0; db < 8; ++db) { f32x4 acc = {0, 0, 0, 0};
; #pragma unroll
;             for (int kk = 0; kk < 4; ++kk) { const bf16x8 bf = *(const bf16x8*)(VTL + (16 * db + lr) * PW + 32 * kk + 8 * lq); acc = mfma16(bf, af[kk], acc); }
;             const int col = g * 128 + 16 * db + 4 * lq; const f32x4 gv = *(const f32x4*)(p.a_g_v + jl * DM + col);
;             bf16_t* up = uv + (size_t)tok * 2048 + col; const u32x2 uu = *(const u32x2*)up;
;             const float u0 = __uint_as_float(uu.x << 16), u1 = __uint_as_float(uu.x & 0xffff0000u), u2 = __uint_as_float(uu.y << 16), u3 = __uint_as_float(uu.y & 0xffff0000u);
;             const f32x4 sv = acc * gv + bs; u32x2 o; o.x = cvt_pk_bf16(u0 * sv[0], u1 * sv[1]); o.y = cvt_pk_bf16(u2 * sv[2], u3 * sv[3]);
;             *(u32x2*)up = o; }
.LBB0_287:
	s_or_b64 exec, exec, s[16:17]
	v_readlane_b32 s6, v254, 42
	s_add_i32 s23, s23, s34
	s_add_i32 s22, s22, s92
	s_add_i32 s21, s21, s6
	s_cmpk_lt_i32 s23, 0x800
	s_waitcnt lgkmcnt(0)
	s_barrier
	ds_read_b128 v[6:9], v50
	s_waitcnt vmcnt(21) lgkmcnt(0)
	v_pk_mul_f32 v[102:103], v[102:103], v[8:9]
	v_pk_mul_f32 v[100:101], v[100:101], v[6:7]
	v_pk_mul_f32 v[106:107], v[106:107], v[8:9]
	v_pk_mul_f32 v[104:105], v[104:105], v[6:7]
	v_pk_mul_f32 v[110:111], v[110:111], v[8:9]
	v_pk_mul_f32 v[108:109], v[108:109], v[6:7]
	v_pk_mul_f32 v[114:115], v[114:115], v[8:9]
	v_pk_mul_f32 v[112:113], v[112:113], v[6:7]
	v_pk_mul_f32 v[118:119], v[118:119], v[8:9]
	v_pk_mul_f32 v[116:117], v[116:117], v[6:7]
	v_pk_mul_f32 v[122:123], v[122:123], v[8:9]
	v_pk_mul_f32 v[120:121], v[120:121], v[6:7]
	v_pk_mul_f32 v[126:127], v[126:127], v[8:9]
	v_pk_mul_f32 v[124:125], v[124:125], v[6:7]
	v_pk_mul_f32 v[130:131], v[130:131], v[8:9]
	v_pk_mul_f32 v[128:129], v[128:129], v[6:7]
	v_cvt_pk_bf16_f32 v100, v100, v101
	v_cvt_pk_bf16_f32 v101, v102, v103
	v_cvt_pk_bf16_f32 v104, v104, v105
	v_cvt_pk_bf16_f32 v105, v106, v107
	v_cvt_pk_bf16_f32 v108, v108, v109
	v_cvt_pk_bf16_f32 v109, v110, v111
	v_cvt_pk_bf16_f32 v112, v112, v113
	v_cvt_pk_bf16_f32 v113, v114, v115
	v_cvt_pk_bf16_f32 v116, v116, v117
	v_cvt_pk_bf16_f32 v117, v118, v119
	v_cvt_pk_bf16_f32 v120, v120, v121
	v_cvt_pk_bf16_f32 v121, v122, v123
	v_cvt_pk_bf16_f32 v124, v124, v125
	v_cvt_pk_bf16_f32 v125, v126, v127
	v_cvt_pk_bf16_f32 v128, v128, v129
	v_cvt_pk_bf16_f32 v129, v130, v131
	ds_write_b64 v54, v[100:101]
	ds_write_b64 v55, v[104:105]
	ds_write_b64 v56, v[108:109]
	ds_write_b64 v57, v[112:113]
	ds_write_b64 v58, v[116:117]
	ds_write_b64 v59, v[120:121]
	ds_write_b64 v60, v[124:125]
	ds_write_b64 v61, v[128:129]
	s_waitcnt vmcnt(17)
	ds_write_b16 v62, v140 offset:34816
	ds_write_b16_d16_hi v62, v140 offset:35088
	ds_write_b16 v62, v141 offset:35360
	ds_write_b16_d16_hi v62, v141 offset:35632
	ds_write_b16 v62, v142 offset:35904
	ds_write_b16_d16_hi v62, v142 offset:36176
	ds_write_b16 v62, v143 offset:36448
	ds_write_b16_d16_hi v63, v143 offset:34816
	ds_write_b16 v64, v144 offset:34816
	ds_write_b16_d16_hi v64, v144 offset:35088
	ds_write_b16 v64, v145 offset:35360
	ds_write_b16_d16_hi v64, v145 offset:35632
	ds_write_b16 v64, v146 offset:35904
	ds_write_b16_d16_hi v64, v146 offset:36176
	ds_write_b16 v64, v147 offset:36448
	ds_write_b16_d16_hi v65, v147 offset:34816
	ds_write_b16 v66, v148 offset:34816
	ds_write_b16_d16_hi v66, v148 offset:35088
	ds_write_b16 v66, v149 offset:35360
	ds_write_b16_d16_hi v66, v149 offset:35632
	ds_write_b16 v66, v150 offset:35904
	ds_write_b16_d16_hi v66, v150 offset:36176
	ds_write_b16 v66, v151 offset:36448
	ds_write_b16_d16_hi v67, v151 offset:34816
	ds_write_b16 v68, v152 offset:34816
	ds_write_b16_d16_hi v68, v152 offset:35088
	ds_write_b16 v68, v153 offset:35360
	ds_write_b16_d16_hi v68, v153 offset:35632
	ds_write_b16 v68, v154 offset:35904
	ds_write_b16_d16_hi v68, v154 offset:36176
	ds_write_b16 v68, v155 offset:36448
	ds_write_b16_d16_hi v69, v155 offset:34816
	s_waitcnt lgkmcnt(0)
	s_barrier
	ds_read_b128 v[14:17], v70
	ds_read_b128 v[10:13], v70 offset:64
	ds_read_b128 v[6:9], v70 offset:128
	ds_read_b128 v[2:5], v70 offset:192
	ds_read_b128 v[72:75], v71 offset:34816
	ds_read_b128 v[76:79], v71 offset:34880
	s_waitcnt lgkmcnt(1)
	v_mfma_f32_16x16x32_bf16 v[72:75], v[72:75], v[14:17], 0
	s_waitcnt lgkmcnt(0)
	v_mfma_f32_16x16x32_bf16 v[72:75], v[76:79], v[10:13], v[72:75]
	ds_read_b128 v[76:79], v71 offset:34944
	s_waitcnt lgkmcnt(0)
	v_mfma_f32_16x16x32_bf16 v[72:75], v[76:79], v[6:9], v[72:75]
	ds_read_b128 v[76:79], v71 offset:35008
	s_waitcnt lgkmcnt(0)
	v_mfma_f32_16x16x32_bf16 v[74:77], v[76:79], v[2:5], v[72:75]
	s_nop 4
	s_waitcnt vmcnt(14)
	s_nop 7
	v_pk_fma_f32 v[74:75], v[74:75], v[180:181], v[46:47] op_sel_hi:[1,1,0]
	v_lshlrev_b32_e32 v78, 16, v156
	v_and_b32_e32 v79, 0xffff0000, v156
	v_pk_fma_f32 v[76:77], v[76:77], v[182:183], v[46:47] op_sel_hi:[1,1,0]
	v_pk_mul_f32 v[74:75], v[74:75], v[78:79]
	v_lshlrev_b32_e32 v78, 16, v157
	v_and_b32_e32 v79, 0xffff0000, v157
	v_pk_mul_f32 v[76:77], v[76:77], v[78:79]
	v_cvt_pk_bf16_f32 v74, v74, v75
	v_cvt_pk_bf16_f32 v75, v76, v77
	global_store_dwordx2 v[48:49], v[74:75], off
	ds_read_b128 v[74:77], v71 offset:39168
	ds_read_b128 v[78:81], v71 offset:39232
	s_waitcnt lgkmcnt(1)
	v_mfma_f32_16x16x32_bf16 v[74:77], v[74:77], v[14:17], 0
	s_waitcnt lgkmcnt(0)
	v_mfma_f32_16x16x32_bf16 v[74:77], v[78:81], v[10:13], v[74:77]
	ds_read_b128 v[78:81], v71 offset:39296
	s_waitcnt lgkmcnt(0)
	v_mfma_f32_16x16x32_bf16 v[74:77], v[78:81], v[6:9], v[74:77]
	ds_read_b128 v[78:81], v71 offset:39360
	s_waitcnt lgkmcnt(0)
	v_mfma_f32_16x16x32_bf16 v[74:77], v[78:81], v[2:5], v[74:77]
	s_waitcnt vmcnt(13)
	s_nop 7
	s_nop 4
	v_pk_fma_f32 v[74:75], v[74:75], v[184:185], v[46:47] op_sel_hi:[1,1,0]
	v_lshlrev_b32_e32 v78, 16, v158
	v_and_b32_e32 v79, 0xffff0000, v158
	v_pk_fma_f32 v[76:77], v[76:77], v[186:187], v[46:47] op_sel_hi:[1,1,0]
	v_pk_mul_f32 v[74:75], v[74:75], v[78:79]
	v_lshlrev_b32_e32 v78, 16, v159
	v_and_b32_e32 v79, 0xffff0000, v159
	v_pk_mul_f32 v[76:77], v[76:77], v[78:79]
	v_cvt_pk_bf16_f32 v74, v74, v75
	v_cvt_pk_bf16_f32 v75, v76, v77
	global_store_dwordx2 v[48:49], v[74:75], off offset:32
	ds_read_b128 v[74:77], v71 offset:43520
	ds_read_b128 v[78:81], v71 offset:43584
	s_waitcnt lgkmcnt(1)
	v_mfma_f32_16x16x32_bf16 v[74:77], v[74:77], v[14:17], 0
	s_waitcnt lgkmcnt(0)
	v_mfma_f32_16x16x32_bf16 v[74:77], v[78:81], v[10:13], v[74:77]
	ds_read_b128 v[78:81], v71 offset:43648
	s_waitcnt lgkmcnt(0)
; __device__ __forceinline__ unsigned cvt_pk_bf16(float lo, float hi) { const f2_t v = {lo, hi}; const bf2_t b = __builtin_convertvector(v, bf2_t); return __builtin_bit_cast(unsigned, b); }
; __device__ __forceinline__ f32x4 mfma16(bf16x8 a, bf16x8 b, f32x4 c) { return __builtin_amdgcn_mfma_f32_16x16x32_bf16(a, b, c, 0, 0, 0); }
; __device__ void sg_phase(int wv, const Params& p, int jl, unsigned char* lds) {
;     ...
;         for (int db = 0; db < 8; ++db) { f32x4 acc = {0, 0, 0, 0};
; #pragma unroll
;             for (int kk = 0; kk < 4; ++kk) { const bf16x8 bf = *(const bf16x8*)(VTL + (16 * db + lr) * PW + 32 * kk + 8 * lq); acc = mfma16(bf, af[kk], acc); }
;             const int col = g * 128 + 16 * db + 4 * lq; const f32x4 gv = *(const f32x4*)(p.a_g_v + jl * DM + col);
;             bf16_t* up = uv + (size_t)tok * 2048 + col; const u32x2 uu = *(const u32x2*)up;
;             const float u0 = __uint_as_float(uu.x << 16), u1 = __uint_as_float(uu.x & 0xffff0000u), u2 = __uint_as_float(uu.y << 16), u3 = __uint_as_float(uu.y & 0xffff0000u);
;             const f32x4 sv = acc * gv + bs; u32x2 o; o.x = cvt_pk_bf16(u0 * sv[0], u1 * sv[1]); o.y = cvt_pk_bf16(u2 * sv[2], u3 * sv[3]);
;             *(u32x2*)up = o; }
;         __syncthreads();
	v_mfma_f32_16x16x32_bf16 v[74:77], v[78:81], v[6:9], v[74:77]
	ds_read_b128 v[78:81], v71 offset:43712
	s_waitcnt lgkmcnt(0)
	v_mfma_f32_16x16x32_bf16 v[74:77], v[78:81], v[2:5], v[74:77]
	s_waitcnt vmcnt(12)
	s_nop 7
	s_nop 4
	v_pk_fma_f32 v[74:75], v[74:75], v[188:189], v[46:47] op_sel_hi:[1,1,0]
	v_lshlrev_b32_e32 v78, 16, v160
	v_and_b32_e32 v79, 0xffff0000, v160
	v_pk_fma_f32 v[76:77], v[76:77], v[190:191], v[46:47] op_sel_hi:[1,1,0]
	v_pk_mul_f32 v[74:75], v[74:75], v[78:79]
	v_lshlrev_b32_e32 v78, 16, v161
	v_and_b32_e32 v79, 0xffff0000, v161
	v_pk_mul_f32 v[76:77], v[76:77], v[78:79]
	v_cvt_pk_bf16_f32 v74, v74, v75
	v_cvt_pk_bf16_f32 v75, v76, v77
	global_store_dwordx2 v[48:49], v[74:75], off offset:64
	ds_read_b128 v[74:77], v71 offset:47872
	ds_read_b128 v[78:81], v71 offset:47936
	s_waitcnt lgkmcnt(1)
	v_mfma_f32_16x16x32_bf16 v[74:77], v[74:77], v[14:17], 0
	s_waitcnt lgkmcnt(0)
	v_mfma_f32_16x16x32_bf16 v[74:77], v[78:81], v[10:13], v[74:77]
	ds_read_b128 v[78:81], v71 offset:48000
	s_waitcnt lgkmcnt(0)
	v_mfma_f32_16x16x32_bf16 v[74:77], v[78:81], v[6:9], v[74:77]
	ds_read_b128 v[78:81], v71 offset:48064
	s_waitcnt lgkmcnt(0)
	v_mfma_f32_16x16x32_bf16 v[74:77], v[78:81], v[2:5], v[74:77]
	s_waitcnt vmcnt(11)
	s_nop 7
	s_nop 4
	v_pk_fma_f32 v[74:75], v[74:75], v[192:193], v[46:47] op_sel_hi:[1,1,0]
	v_lshlrev_b32_e32 v78, 16, v162
	v_and_b32_e32 v79, 0xffff0000, v162
	v_pk_fma_f32 v[76:77], v[76:77], v[194:195], v[46:47] op_sel_hi:[1,1,0]
	v_pk_mul_f32 v[74:75], v[74:75], v[78:79]
	v_lshlrev_b32_e32 v78, 16, v163
	v_and_b32_e32 v79, 0xffff0000, v163
	v_pk_mul_f32 v[76:77], v[76:77], v[78:79]
	v_cvt_pk_bf16_f32 v74, v74, v75
	v_cvt_pk_bf16_f32 v75, v76, v77
	global_store_dwordx2 v[48:49], v[74:75], off offset:96
	ds_read_b128 v[74:77], v71 offset:52224
	ds_read_b128 v[78:81], v71 offset:52288
	s_waitcnt lgkmcnt(1)
	v_mfma_f32_16x16x32_bf16 v[74:77], v[74:77], v[14:17], 0
	s_waitcnt lgkmcnt(0)
	v_mfma_f32_16x16x32_bf16 v[74:77], v[78:81], v[10:13], v[74:77]
	ds_read_b128 v[78:81], v71 offset:52352
	s_waitcnt lgkmcnt(0)
	v_mfma_f32_16x16x32_bf16 v[74:77], v[78:81], v[6:9], v[74:77]
	ds_read_b128 v[78:81], v71 offset:52416
	s_waitcnt lgkmcnt(0)
	v_mfma_f32_16x16x32_bf16 v[74:77], v[78:81], v[2:5], v[74:77]
	s_waitcnt vmcnt(10)
	s_nop 7
	s_nop 4
	v_pk_fma_f32 v[74:75], v[74:75], v[196:197], v[46:47] op_sel_hi:[1,1,0]
	v_lshlrev_b32_e32 v78, 16, v164
	v_and_b32_e32 v79, 0xffff0000, v164
	v_pk_fma_f32 v[76:77], v[76:77], v[198:199], v[46:47] op_sel_hi:[1,1,0]
	v_pk_mul_f32 v[74:75], v[74:75], v[78:79]
	v_lshlrev_b32_e32 v78, 16, v165
	v_and_b32_e32 v79, 0xffff0000, v165
	v_pk_mul_f32 v[76:77], v[76:77], v[78:79]
	v_cvt_pk_bf16_f32 v74, v74, v75
	v_cvt_pk_bf16_f32 v75, v76, v77
	global_store_dwordx2 v[48:49], v[74:75], off offset:128
	ds_read_b128 v[74:77], v71 offset:56576
	ds_read_b128 v[78:81], v71 offset:56640
	s_waitcnt lgkmcnt(1)
	v_mfma_f32_16x16x32_bf16 v[74:77], v[74:77], v[14:17], 0
	s_waitcnt lgkmcnt(0)
	v_mfma_f32_16x16x32_bf16 v[74:77], v[78:81], v[10:13], v[74:77]
	ds_read_b128 v[78:81], v71 offset:56704
	s_waitcnt lgkmcnt(0)
	v_mfma_f32_16x16x32_bf16 v[74:77], v[78:81], v[6:9], v[74:77]
	ds_read_b128 v[78:81], v71 offset:56768
	s_waitcnt lgkmcnt(0)
	v_mfma_f32_16x16x32_bf16 v[74:77], v[78:81], v[2:5], v[74:77]
	s_waitcnt vmcnt(9)
	s_nop 7
	s_nop 4
	v_pk_fma_f32 v[74:75], v[74:75], v[200:201], v[46:47] op_sel_hi:[1,1,0]
	v_lshlrev_b32_e32 v78, 16, v166
	v_and_b32_e32 v79, 0xffff0000, v166
	v_pk_fma_f32 v[76:77], v[76:77], v[202:203], v[46:47] op_sel_hi:[1,1,0]
	v_pk_mul_f32 v[74:75], v[74:75], v[78:79]
	v_lshlrev_b32_e32 v78, 16, v167
	v_and_b32_e32 v79, 0xffff0000, v167
	v_pk_mul_f32 v[76:77], v[76:77], v[78:79]
	v_cvt_pk_bf16_f32 v74, v74, v75
	v_cvt_pk_bf16_f32 v75, v76, v77
	global_store_dwordx2 v[48:49], v[74:75], off offset:160
	ds_read_b128 v[74:77], v71 offset:60928
	ds_read_b128 v[78:81], v71 offset:60992
	s_waitcnt lgkmcnt(1)
	v_mfma_f32_16x16x32_bf16 v[74:77], v[74:77], v[14:17], 0
	s_waitcnt lgkmcnt(0)
	v_mfma_f32_16x16x32_bf16 v[74:77], v[78:81], v[10:13], v[74:77]
	ds_read_b128 v[78:81], v71 offset:61056
	s_waitcnt lgkmcnt(0)
	v_mfma_f32_16x16x32_bf16 v[74:77], v[78:81], v[6:9], v[74:77]
	ds_read_b128 v[78:81], v71 offset:61120
	s_waitcnt lgkmcnt(0)
	v_mfma_f32_16x16x32_bf16 v[74:77], v[78:81], v[2:5], v[74:77]
	s_waitcnt vmcnt(8)
	s_nop 7
	s_nop 4
	v_pk_fma_f32 v[74:75], v[74:75], v[204:205], v[46:47] op_sel_hi:[1,1,0]
	v_lshlrev_b32_e32 v78, 16, v168
	v_and_b32_e32 v79, 0xffff0000, v168
	v_pk_fma_f32 v[76:77], v[76:77], v[206:207], v[46:47] op_sel_hi:[1,1,0]
	v_pk_mul_f32 v[74:75], v[74:75], v[78:79]
	v_lshlrev_b32_e32 v78, 16, v169
	v_and_b32_e32 v79, 0xffff0000, v169
	v_pk_mul_f32 v[76:77], v[76:77], v[78:79]
	v_cvt_pk_bf16_f32 v74, v74, v75
	v_cvt_pk_bf16_f32 v75, v76, v77
	global_store_dwordx2 v[48:49], v[74:75], off offset:192
	ds_read_b128 v[74:77], v71 offset:65280
	s_waitcnt lgkmcnt(0)
	v_mfma_f32_16x16x32_bf16 v[14:17], v[74:77], v[14:17], 0
	ds_read_b128 v[74:77], v71 offset:65344
	s_waitcnt lgkmcnt(0)
	v_mfma_f32_16x16x32_bf16 v[10:13], v[74:77], v[10:13], v[14:17]
	s_nop 4
	ds_read_b128 v[14:17], v71 offset:65408
	s_waitcnt lgkmcnt(0)
	v_mfma_f32_16x16x32_bf16 v[6:9], v[14:17], v[6:9], v[10:13]
	s_nop 2
	ds_read_b128 v[10:13], v71 offset:65472
	s_waitcnt lgkmcnt(0)
	v_mfma_f32_16x16x32_bf16 v[2:5], v[10:13], v[2:5], v[6:9]
	s_nop 2
	s_waitcnt vmcnt(7)
	s_nop 7
	s_nop 1
	v_pk_fma_f32 v[2:3], v[2:3], v[208:209], v[46:47] op_sel_hi:[1,1,0]
	v_lshlrev_b32_e32 v6, 16, v170
	v_and_b32_e32 v7, 0xffff0000, v170
	v_pk_fma_f32 v[4:5], v[4:5], v[210:211], v[46:47] op_sel_hi:[1,1,0]
	v_pk_mul_f32 v[2:3], v[2:3], v[6:7]
	v_lshlrev_b32_e32 v6, 16, v171
	v_and_b32_e32 v7, 0xffff0000, v171
	v_pk_mul_f32 v[4:5], v[4:5], v[6:7]
	v_cvt_pk_bf16_f32 v2, v2, v3
	v_cvt_pk_bf16_f32 v3, v4, v5
	global_store_dwordx2 v[48:49], v[2:3], off offset:224
	s_barrier
	s_cbranch_scc0 .LBB0_290
; __device__ __forceinline__ unsigned cvt_pk_bf16(float lo, float hi) { const f2_t v = {lo, hi}; const bf2_t b = __builtin_convertvector(v, bf2_t); return __builtin_bit_cast(unsigned, b); }
; __device__ __forceinline__ f32x4 mfma16(bf16x8 a, bf16x8 b, f32x4 c) { return __builtin_amdgcn_mfma_f32_16x16x32_bf16(a, b, c, 0, 0, 0); }
; __device__ void sg_phase(int wv, const Params& p, int jl, unsigned char* lds) {
;     ...
;     for (int unit = blockIdx.x; unit < 2048; unit += gridDim.x) {
;         const int ch = unit >> 3, g = unit & 7, t0 = ch * 128;
;         if (tid < 128) rsL[tid] = 1.0f / sqrtf((float)vss[t0 + tid] * SSKI + EPSN);
;         __syncthreads();
;         const float* ws = p.a_w_s + ((size_t)jl * 8 + g) * 128 * 128;
; #pragma unroll
;         for (int ps = 0; ps < 8; ++ps) { const int idx = tid + ps * NTHR, t = idx >> 5, s4 = (idx & 31) * 4;
;             const f32x4 wv = *(const f32x4*)(ws + t * 128 + s4); const f32x4 r4 = *(const f32x4*)(rsL + s4); const f32x4 x = wv * r4;
;             u32x2 pk; pk.x = cvt_pk_bf16(x[0], x[1]); pk.y = cvt_pk_bf16(x[2], x[3]); *(u32x2*)(WsL + t * PW + s4) = pk; }
; #pragma unroll
;         for (int ps = 0; ps < 4; ++ps) { const int idx = tid + ps * NTHR, s = idx & 127, d8 = (idx >> 7) * 8;
;             const bf16x8 v = *(const bf16x8*)(uv + (size_t)(t0 + s) * 2048 + 1024 + g * 128 + d8);
; #pragma unroll
;             for (int e = 0; e < 8; ++e) VTL[(d8 + e) * PW + s] = (bf16_t)v[e]; }
;         __syncthreads();
;         bf16x8 af[4];
; #pragma unroll
;         for (int kk = 0; kk < 4; ++kk) af[kk] = *(const bf16x8*)(WsL + (16 * w + lr) * PW + 32 * kk + 8 * lq);
;         const int tok = t0 + 16 * w + lr; const float bs = p.a_b_s[((size_t)jl * 8 + g) * 128 + 16 * w + lr];
; #pragma unroll
;         for (int db = 0; db < 8; ++db) { f32x4 acc = {0, 0, 0, 0};
; #pragma unroll
;             for (int kk = 0; kk < 4; ++kk) { const bf16x8 bf = *(const bf16x8*)(VTL + (16 * db + lr) * PW + 32 * kk + 8 * lq); acc = mfma16(bf, af[kk], acc); }
;             const int col = g * 128 + 16 * db + 4 * lq; const f32x4 gv = *(const f32x4*)(p.a_g_v + jl * DM + col);
;             bf16_t* up = uv + (size_t)tok * 2048 + col; const u32x2 uu = *(const u32x2*)up;
.LBB0_288:
	s_and_b32 s42, s21, 0xffffff80
	s_and_b32 s6, s22, 0x380
	s_or_b32 s7, s20, s6
	s_lshl_b32 s36, s7, 9
	v_lshl_add_u64 v[10:11], v[42:43], 0, s[36:37]
	v_lshl_add_u64 v[84:85], v[18:19], 2, v[10:11]
	global_load_dwordx4 v[100:103], v[84:85], off
	v_lshl_add_u64 v[86:87], v[20:21], 2, v[10:11]
	global_load_dwordx4 v[104:107], v[86:87], off
	v_lshl_add_u64 v[88:89], v[22:23], 2, v[10:11]
	global_load_dwordx4 v[108:111], v[88:89], off
	v_lshl_add_u64 v[90:91], v[24:25], 2, v[10:11]
	global_load_dwordx4 v[112:115], v[90:91], off
	v_lshl_add_u64 v[92:93], v[26:27], 2, v[10:11]
	global_load_dwordx4 v[116:119], v[92:93], off
	v_lshl_add_u64 v[94:95], v[28:29], 2, v[10:11]
	global_load_dwordx4 v[120:123], v[94:95], off
	v_lshl_add_u64 v[96:97], v[30:31], 2, v[10:11]
	global_load_dwordx4 v[124:127], v[96:97], off
	v_lshl_add_u64 v[98:99], v[32:33], 2, v[10:11]
	global_load_dwordx4 v[128:131], v[98:99], off
	s_lshl_b32 s36, s6, 1
	v_add_u32_e32 v48, s42, v52
	v_ashrrev_i32_e32 v49, 31, v48
	v_or_b32_e32 v82, s6, v53
	v_lshlrev_b64 v[48:49], 12, v[48:49]
	v_lshl_add_u64 v[48:49], s[76:77], 0, v[48:49]
	v_mov_b32_e32 v83, v0
	v_or_b32_e32 v2, s42, v51
	v_ashrrev_i32_e32 v3, 31, v2
	v_lshlrev_b64 v[2:3], 12, v[2:3]
	v_lshl_add_u64 v[2:3], s[76:77], 0, v[2:3]
	v_lshl_add_u64 v[6:7], v[2:3], 0, s[36:37]
	v_lshl_add_u64 v[132:133], v[34:35], 1, v[6:7]
	global_load_dwordx4 v[140:143], v[132:133], off offset:2048
	v_lshl_add_u64 v[134:135], v[36:37], 1, v[6:7]
	global_load_dwordx4 v[144:147], v[134:135], off offset:2048
	v_lshl_add_u64 v[136:137], v[38:39], 1, v[6:7]
	global_load_dwordx4 v[148:151], v[136:137], off offset:2048
	v_lshl_add_u64 v[138:139], v[40:41], 1, v[6:7]
	global_load_dwordx4 v[152:155], v[138:139], off offset:2048
	s_lshl_b32 s36, s7, 2
	v_lshl_add_u64 v[72:73], v[44:45], 0, s[36:37]
	global_load_dword v46, v[72:73], off
	v_lshlrev_b32_e32 v72, 2, v82
	v_lshlrev_b32_e32 v82, 1, v82
	v_lshl_add_u64 v[48:49], v[48:49], 0, v[82:83]
	global_load_dwordx4 v[180:183], v72, s[14:15]
	global_load_dwordx2 v[156:157], v[48:49], off
	global_load_dwordx4 v[184:187], v72, s[14:15] offset:64
	global_load_dwordx2 v[158:159], v[48:49], off offset:32
	global_load_dwordx4 v[188:191], v72, s[14:15] offset:128
	global_load_dwordx2 v[160:161], v[48:49], off offset:64
	global_load_dwordx4 v[192:195], v72, s[14:15] offset:192
	global_load_dwordx2 v[162:163], v[48:49], off offset:96
	global_load_dwordx4 v[196:199], v72, s[14:15] offset:256
	global_load_dwordx2 v[164:165], v[48:49], off offset:128
	global_load_dwordx4 v[200:203], v72, s[14:15] offset:320
	global_load_dwordx2 v[166:167], v[48:49], off offset:160
	global_load_dwordx4 v[204:207], v72, s[14:15] offset:384
	global_load_dwordx2 v[168:169], v[48:49], off offset:192
	global_load_dwordx4 v[208:211], v72, s[14:15] offset:448
	global_load_dwordx2 v[170:171], v[48:49], off offset:224
	s_and_saveexec_b64 s[16:17], s[4:5]
	s_cbranch_execz .LBB0_287
	v_add_u32_e32 v2, s42, v1
	v_ashrrev_i32_e32 v3, 31, v2
	v_lshl_add_u64 v[2:3], v[2:3], 3, s[10:11]
	global_load_dwordx2 v[2:3], v[2:3], off
	s_mov_b32 s6, 0xf800000
	s_waitcnt vmcnt(0)
	v_ffbh_u32_e32 v4, v3
	v_min_u32_e32 v4, 32, v4
	v_lshlrev_b64 v[2:3], v4, v[2:3]
	v_min_u32_e32 v2, 1, v2
	v_or_b32_e32 v2, v3, v2
	v_cvt_f32_u32_e32 v2, v2
	v_sub_u32_e32 v3, 32, v4
	v_ldexp_f32 v2, v2, v3
	v_fmamk_f32 v2, v2, 0x30800000, v251
	v_mul_f32_e32 v3, 0x4f800000, v2
	v_cmp_gt_f32_e32 vcc, s6, v2
	s_nop 1
	v_cndmask_b32_e32 v2, v2, v3, vcc
	v_sqrt_f32_e32 v3, v2
	s_nop 0
	v_add_u32_e32 v4, -1, v3
	v_add_u32_e32 v5, 1, v3
	v_fma_f32 v6, -v4, v3, v2
	v_fma_f32 v7, -v5, v3, v2
	v_cmp_ge_f32_e64 s[6:7], 0, v6
	s_nop 1
	v_cndmask_b32_e64 v3, v3, v4, s[6:7]
	v_cmp_lt_f32_e64 s[6:7], 0, v7
	s_nop 1
	v_cndmask_b32_e64 v3, v3, v5, s[6:7]
	v_mul_f32_e32 v4, 0x37800000, v3
	v_cndmask_b32_e32 v3, v3, v4, vcc
	v_mov_b32_e32 v4, 0x260
	v_cmp_class_f32_e32 vcc, v2, v4
	s_nop 1
	v_cndmask_b32_e32 v2, v3, v2, vcc
	v_div_scale_f32 v3, s[6:7], v2, v2, 1.0
	v_rcp_f32_e32 v4, v3
	v_div_scale_f32 v5, vcc, 1.0, v2, 1.0
	v_fma_f32 v6, -v3, v4, 1.0
	v_fmac_f32_e32 v4, v6, v4
	v_mul_f32_e32 v6, v5, v4
	v_fma_f32 v7, -v3, v6, v5
	v_fmac_f32_e32 v6, v7, v4
	v_fma_f32 v3, -v3, v6, v5
	v_div_fmas_f32 v3, v3, v4, v6
	v_div_fixup_f32 v2, v3, v2, 1.0
	ds_write_b32 v47, v2
	s_branch .LBB0_287
